# attention: five aligned pairs of first-half p1 v_fmamk_f32 packed into v_pk_fma_f32 (5 VALU fewer per two tiles), on top of v18
# baseline (speedup 1.0000x reference)
; #define SBAR() __builtin_amdgcn_sched_barrier(0)
; #define SLOAD(i, k0) do { sr_[i].vs0 = St::ld8(&Vh[(long)((k0) + sr) * LDK + sc]); sr_[i].vs1 = St::ld8(&Vh[(long)((k0) + 32 + sr) * LDK + sc]); \
;     sr_[i].ks0 = St::ld8(&Kh[(long)((k0) + sr) * LDK + sc]); sr_[i].ks1 = St::ld8(&Kh[(long)((k0) + 32 + sr) * LDK + sc]); } while (0)
; __device__ __forceinline__ void partialSM(f32x16& p0, f32x16& p1, float& m_reg, float& mn, float& alpha) {
;     ...
;   float mnC = -mn * C;
;   for (int r = 0; r < 16; ++r) p0[r] = fmaf(p0[r], C, mnC); for (int r = 0; r < 16; ++r) p1[r] = fmaf(p1[r], C, mnC);
;   for (int r = 0; r < 16; ++r) p0[r] = __builtin_amdgcn_exp2f(p0[r]);
; }
; __device__ __forceinline__ void finishSM(f32x16& p0, f32x16& p1, float alpha, float& l_reg, bf16x8& pa0, bf16x8& pa1, bf16x8& pa2, bf16x8& pa3) {
;   for (int r = 0; r < 16; ++r) p1[r] = __builtin_amdgcn_exp2f(p1[r]);
;   float ps = 0; for (int r = 0; r < 16; ++r) ps += p0[r]; for (int r = 0; r < 16; ++r) ps += p1[r];
;   { auto rr = __builtin_amdgcn_permlane32_swap(__float_as_uint(ps), __float_as_uint(ps), false, false);
;     ps = __uint_as_float(rr[0]) + __uint_as_float(rr[1]); }
;   l_reg = l_reg * alpha + ps;
;     ...
;   PK4(p0, 0, pa0); PK4(p0, 8, pa1); PK4(p1, 0, pa2); PK4(p1, 8, pa3);
;     ...
; }
; __device__ __forceinline__ void qkt(f32x16& p0, f32x16& p1, const bf16* Ks, const bf16x8* qr, int r32, int hi) {
;   p0 = f32x16{}; p1 = f32x16{};
;   for (int d0 = 0; d0 < 8; ++d0) { int cb = (d0 * 16 + hi * 8) * 2;
;     bf16x8 b0 = *reinterpret_cast<const bf16x8*>((const char*)Ks + KSWZ(r32, cb));
;     bf16x8 b1 = *reinterpret_cast<const bf16x8*>((const char*)Ks + KSWZ(32 + r32, cb));
;     p0 = __builtin_amdgcn_mfma_f32_32x32x16_bf16(b0, qr[d0], p0, 0, 0, 0);
;     p1 = __builtin_amdgcn_mfma_f32_32x32x16_bf16(b1, qr[d0], p1, 0, 0, 0); }
; template <typename TQ>
; __device__ __forceinline__ void attn_dense_body(const TQ* __restrict__ Qb, const bf16* __restrict__ Kh, const bf16* __restrict__ Vh,
;                                                 unsigned short* __restrict__ Ob, int seq, char* lds, const int wave_s) {
;     ...
;     if (SDEPTH == 1 || j + 3 < NT) SLOAD(SE, (j + 1 + SDEPTH) * KVBLK); SBAR();
.LBB0_579:
	v_xor_b32_e32 v189, 0x18000, v189
	v_xor_b32_e32 v199, 0x18000, v199
	v_xor_b32_e32 v192, 0x18000, v192
	v_xor_b32_e32 v191, 0x18000, v191
	v_mul_f32_e32 v207, 0xbe0293ee, v206
	v_fmamk_f32 v80, v80, 0x3e0293ee, v207
	v_fmamk_f32 v81, v81, 0x3e0293ee, v207
	v_fmamk_f32 v82, v82, 0x3e0293ee, v207
	v_fmamk_f32 v83, v83, 0x3e0293ee, v207
	v_fmamk_f32 v84, v84, 0x3e0293ee, v207
	v_fmamk_f32 v85, v85, 0x3e0293ee, v207
	v_fmamk_f32 v86, v86, 0x3e0293ee, v207
	v_fmamk_f32 v87, v87, 0x3e0293ee, v207
	v_fmamk_f32 v88, v88, 0x3e0293ee, v207
	v_fmamk_f32 v89, v89, 0x3e0293ee, v207
	v_fmamk_f32 v90, v90, 0x3e0293ee, v207
	v_fmamk_f32 v91, v91, 0x3e0293ee, v207
	v_fmamk_f32 v92, v92, 0x3e0293ee, v207
	v_fmamk_f32 v93, v93, 0x3e0293ee, v207
	v_fmamk_f32 v94, v94, 0x3e0293ee, v207
	v_fmamk_f32 v95, v95, 0x3e0293ee, v207
	v_exp_f32_e32 v160, v80
	v_exp_f32_e32 v175, v81
	v_exp_f32_e32 v161, v82
	v_exp_f32_e32 v174, v83
	v_exp_f32_e32 v162, v84
	v_exp_f32_e32 v173, v85
	v_exp_f32_e32 v163, v86
	v_exp_f32_e32 v172, v87
	v_exp_f32_e32 v164, v88
	v_exp_f32_e32 v171, v89
	v_exp_f32_e32 v165, v90
	v_exp_f32_e32 v170, v91
	v_exp_f32_e32 v166, v92
	v_exp_f32_e32 v169, v93
	v_exp_f32_e32 v167, v94
	v_exp_f32_e32 v168, v95
	v_pk_fma_f32 v[216:217], v[64:65], s[30:31], v[206:207] op_sel:[0,0,1] op_sel_hi:[1,0,1]
	v_pk_fma_f32 v[218:219], v[66:67], s[30:31], v[206:207] op_sel:[0,0,1] op_sel_hi:[1,0,1]
	v_fmamk_f32 v224, v68, 0x3e0293ee, v207
	v_fmamk_f32 v209, v69, 0x3e0293ee, v207
	v_pk_fma_f32 v[210:211], v[70:71], s[30:31], v[206:207] op_sel:[0,0,1] op_sel_hi:[1,0,1]
	v_pk_fma_f32 v[212:213], v[72:73], s[30:31], v[206:207] op_sel:[0,0,1] op_sel_hi:[1,0,1]
	v_pk_fma_f32 v[214:215], v[74:75], s[30:31], v[206:207] op_sel:[0,0,1] op_sel_hi:[1,0,1]
	v_fmamk_f32 v208, v76, 0x3e0293ee, v207
	v_fmamk_f32 v225, v77, 0x3e0293ee, v207
	v_fmamk_f32 v226, v78, 0x3e0293ee, v207
	v_fmac_f32_e32 v207, 0x3e0293ee, v79
	s_waitcnt lgkmcnt(0)
	s_barrier
	ds_read_b128 v[64:67], v189 offset:32768
	ds_read_b128 v[68:71], v189 offset:40960
	ds_read_b128 v[228:231], v199 offset:32768
	ds_read_b128 v[232:235], v199 offset:40960
	ds_read_b128 v[240:243], v192 offset:32768
	ds_read_b128 v[244:247], v192 offset:40960
	v_exp_f32_e32 v221, v207
	s_waitcnt lgkmcnt(5)
	v_mfma_f32_32x32x16_bf16 v[80:95], v[64:67], v[112:115], 0
	v_add_f32_e32 v207, v175, v160
	v_add_f32_e32 v207, v161, v207
	v_add_f32_e32 v207, v174, v207
	v_add_f32_e32 v207, v162, v207
	v_add_f32_e32 v207, v173, v207
	v_add_f32_e32 v207, v163, v207
	v_add_f32_e32 v207, v172, v207
	s_waitcnt lgkmcnt(4)
	v_mfma_f32_32x32x16_bf16 v[64:79], v[68:71], v[112:115], 0
	v_add_f32_e32 v207, v164, v207
	v_add_f32_e32 v207, v171, v207
	v_add_f32_e32 v207, v165, v207
	v_add_f32_e32 v207, v170, v207
	v_exp_f32_e32 v194, v216
	v_add_f32_e32 v207, v166, v207
	v_exp_f32_e32 v195, v217
	s_waitcnt lgkmcnt(3)
	v_mfma_f32_32x32x16_bf16 v[80:95], v[228:231], v[108:111], v[80:95]
	v_add_f32_e32 v207, v169, v207
	v_exp_f32_e32 v196, v218
	v_add_f32_e32 v207, v167, v207
	v_exp_f32_e32 v197, v219
	v_add_f32_e32 v207, v168, v207
	v_exp_f32_e32 v216, v224
	v_add_f32_e32 v207, v194, v207
	s_waitcnt lgkmcnt(2)
	v_mfma_f32_32x32x16_bf16 v[64:79], v[232:235], v[108:111], v[64:79]
	ds_read_b128 v[228:231], v191 offset:32768
	ds_read_b128 v[232:235], v191 offset:40960
	v_exp_f32_e32 v209, v209
	v_add_f32_e32 v207, v195, v207
	v_exp_f32_e32 v210, v210
	v_add_f32_e32 v207, v196, v207
	v_exp_f32_e32 v211, v211
	v_add_f32_e32 v207, v197, v207
	s_waitcnt lgkmcnt(3)
	v_mfma_f32_32x32x16_bf16 v[80:95], v[240:243], v[120:123], v[80:95]
	v_exp_f32_e32 v212, v212
	v_add_f32_e32 v207, v216, v207
	v_exp_f32_e32 v213, v213
	v_add_f32_e32 v207, v209, v207
	v_exp_f32_e32 v214, v214
	v_add_f32_e32 v207, v210, v207
	v_exp_f32_e32 v215, v215
	s_waitcnt lgkmcnt(2)
	v_mfma_f32_32x32x16_bf16 v[64:79], v[244:247], v[120:123], v[64:79]
	ds_read_b128 v[240:243], v189 offset:32896
	ds_read_b128 v[244:247], v189 offset:41088
	v_add_f32_e32 v207, v211, v207
	v_exp_f32_e32 v217, v208
	v_add_f32_e32 v207, v212, v207
	v_exp_f32_e32 v218, v225
	v_add_f32_e32 v207, v213, v207
	v_exp_f32_e32 v219, v226
	s_waitcnt lgkmcnt(3)
	v_mfma_f32_32x32x16_bf16 v[80:95], v[228:231], v[124:127], v[80:95]
	v_add_f32_e32 v207, v214, v207
	v_add_f32_e32 v207, v215, v207
	v_add_f32_e32 v207, v217, v207
	v_add_f32_e32 v207, v218, v207
	v_add_f32_e32 v207, v219, v207
	v_add_f32_e32 v207, v221, v207
	s_waitcnt lgkmcnt(2)
	v_mfma_f32_32x32x16_bf16 v[64:79], v[232:235], v[124:127], v[64:79]
	ds_read_b128 v[228:231], v199 offset:32896
	ds_read_b128 v[232:235], v199 offset:41088
	s_waitcnt lgkmcnt(3)
	v_mfma_f32_32x32x16_bf16 v[80:95], v[240:243], v[116:119], v[80:95]
	s_waitcnt lgkmcnt(2)
	v_mfma_f32_32x32x16_bf16 v[64:79], v[244:247], v[116:119], v[64:79]
	ds_read_b128 v[240:243], v192 offset:32896
	ds_read_b128 v[244:247], v192 offset:41088
	s_waitcnt lgkmcnt(3)
	v_mfma_f32_32x32x16_bf16 v[80:95], v[228:231], v[104:107], v[80:95]
	s_waitcnt lgkmcnt(2)
	v_mfma_f32_32x32x16_bf16 v[64:79], v[232:235], v[104:107], v[64:79]
	ds_read_b128 v[228:231], v191 offset:32896
	ds_read_b128 v[232:235], v191 offset:41088
	s_waitcnt lgkmcnt(3)
	v_mfma_f32_32x32x16_bf16 v[80:95], v[240:243], v[100:103], v[80:95]
	s_waitcnt lgkmcnt(2)
	v_mfma_f32_32x32x16_bf16 v[64:79], v[244:247], v[100:103], v[64:79]
	v_cvt_pk_bf16_f32 v160, v160, v175
	v_cvt_pk_bf16_f32 v161, v161, v174
	v_cvt_pk_bf16_f32 v162, v162, v173
	v_cvt_pk_bf16_f32 v163, v163, v172
	v_cvt_pk_bf16_f32 v164, v164, v171
	v_cvt_pk_bf16_f32 v165, v165, v170
	s_waitcnt lgkmcnt(1)
	v_mfma_f32_32x32x16_bf16 v[80:95], v[228:231], v[96:99], v[80:95]
	v_cvt_pk_bf16_f32 v166, v166, v169
	v_cvt_pk_bf16_f32 v167, v167, v168
	v_cvt_pk_bf16_f32 v168, v194, v195
	v_cvt_pk_bf16_f32 v169, v196, v197
	v_cvt_pk_bf16_f32 v170, v216, v209
	v_cvt_pk_bf16_f32 v171, v210, v211
	v_cvt_pk_bf16_f32 v172, v212, v213
	s_waitcnt lgkmcnt(0)
	v_mfma_f32_32x32x16_bf16 v[64:79], v[232:235], v[96:99], v[64:79]
	v_cvt_pk_bf16_f32 v173, v214, v215
	v_cvt_pk_bf16_f32 v174, v217, v218
	v_cvt_pk_bf16_f32 v175, v219, v221
	s_add_i32 s50, s50, 2
	s_cmp_ge_u32 s50, s49
	s_cselect_b64 s[44:45], -1, 0
	s_and_b64 vcc, exec, s[44:45]
	s_cbranch_vccnz .Lattn_skip_loads
	global_load_dwordx4 v[128:131], v176, s[52:53]
	global_load_dwordx4 v[132:135], v176, s[52:53] offset:-512
	s_add_u32 s52, s52, 0x18000
	s_addc_u32 s53, s53, 0
	global_load_dwordx4 v[136:139], v176, s[52:53]
	global_load_dwordx4 v[140:143], v176, s[52:53] offset:-512
	s_add_u32 s52, s52, 0x18000
	s_addc_u32 s53, s53, 0
